# v13: v12 + removed the compiler store-drain s_waitcnt vmcnt(0) in the P5a/P5b/P10 unit preheaders
# baseline (speedup 1.0000x reference)
.LBB0_549:
	s_ashr_i32 s25, s24, 31
	s_lshl_b64 s[26:27], s[24:25], 19
	s_add_u32 s26, s48, s26
	s_addc_u32 s27, s49, s27
	s_and_b64 s[28:29], s[2:3], exec
	s_cselect_b32 s25, s27, s35
	s_cselect_b32 s70, s26, s34
	s_ashr_i32 s23, s22, 31
	s_lshl_b64 s[28:29], s[22:23], 19
	v_readlane_b32 s72, v254, 10
	s_add_u32 s28, s72, s28
	s_addc_u32 s29, s79, s29
	s_and_b64 s[38:39], s[2:3], exec
	s_cselect_b32 s23, s29, s37
	s_cselect_b32 s71, s28, s36
	s_add_u32 s34, s34, 0x40080
	s_addc_u32 s35, s35, 0
	v_readlane_b32 s73, v254, 11
	v_readlane_b32 s74, v254, 12
	s_add_u32 s72, s36, 0x100
	v_mov_b32_e32 v2, 0
	s_addc_u32 s73, s37, 0
	s_mov_b32 s74, -2
	v_mov_b32_e32 v3, v2
	v_mov_b32_e32 v4, v2
	v_mov_b32_e32 v5, v2
	v_mov_b32_e32 v6, v2
	v_mov_b32_e32 v7, v2
	v_mov_b32_e32 v8, v2
	v_mov_b32_e32 v9, v2
	v_mov_b32_e32 v18, v2
	v_mov_b32_e32 v19, v2
	v_mov_b32_e32 v20, v2
	v_mov_b32_e32 v21, v2
	v_mov_b32_e32 v22, v2
	v_mov_b32_e32 v23, v2
	v_mov_b32_e32 v24, v2
	v_mov_b32_e32 v25, v2
	v_mov_b32_e32 v34, v2
	v_mov_b32_e32 v35, v2
	v_mov_b32_e32 v36, v2
	v_mov_b32_e32 v37, v2
	v_mov_b32_e32 v38, v2
	v_mov_b32_e32 v39, v2
	v_mov_b32_e32 v40, v2
	v_mov_b32_e32 v41, v2
	v_mov_b32_e32 v50, v2
	v_mov_b32_e32 v51, v2
	v_mov_b32_e32 v52, v2
	v_mov_b32_e32 v53, v2
	v_mov_b32_e32 v54, v2
	v_mov_b32_e32 v55, v2
	v_mov_b32_e32 v56, v2
	v_mov_b32_e32 v57, v2
	v_mov_b32_e32 v10, v2
	v_mov_b32_e32 v11, v2
	v_mov_b32_e32 v12, v2
	v_mov_b32_e32 v13, v2
	v_mov_b32_e32 v14, v2
	v_mov_b32_e32 v15, v2
	v_mov_b32_e32 v16, v2
	v_mov_b32_e32 v17, v2
	v_mov_b32_e32 v26, v2
	v_mov_b32_e32 v27, v2
	v_mov_b32_e32 v28, v2
	v_mov_b32_e32 v29, v2
	v_mov_b32_e32 v30, v2
	v_mov_b32_e32 v31, v2
	v_mov_b32_e32 v32, v2
	v_mov_b32_e32 v33, v2
	v_mov_b32_e32 v42, v2
	v_mov_b32_e32 v43, v2
	v_mov_b32_e32 v44, v2
	v_mov_b32_e32 v45, v2
	v_mov_b32_e32 v46, v2
	v_mov_b32_e32 v47, v2
	v_mov_b32_e32 v48, v2
	v_mov_b32_e32 v49, v2
	v_mov_b32_e32 v58, v2
	v_mov_b32_e32 v59, v2
	v_mov_b32_e32 v60, v2
	v_mov_b32_e32 v61, v2
	v_mov_b32_e32 v62, v2
	v_mov_b32_e32 v63, v2
	v_mov_b32_e32 v64, v2
	v_mov_b32_e32 v65, v2
	v_mov_b32_e32 v66, v2
	v_mov_b32_e32 v67, v2
	v_mov_b32_e32 v68, v2
	v_mov_b32_e32 v69, v2
	v_mov_b32_e32 v70, v2
	v_mov_b32_e32 v71, v2
	v_mov_b32_e32 v72, v2
	v_mov_b32_e32 v73, v2
	v_mov_b32_e32 v82, v2
	v_mov_b32_e32 v83, v2
	v_mov_b32_e32 v84, v2
	v_mov_b32_e32 v85, v2
	v_mov_b32_e32 v86, v2
	v_mov_b32_e32 v87, v2
	v_mov_b32_e32 v88, v2
	v_mov_b32_e32 v89, v2
	v_mov_b32_e32 v98, v2
	v_mov_b32_e32 v99, v2
	v_mov_b32_e32 v100, v2
	v_mov_b32_e32 v101, v2
	v_mov_b32_e32 v102, v2
	v_mov_b32_e32 v103, v2
	v_mov_b32_e32 v104, v2
	v_mov_b32_e32 v105, v2
	v_mov_b32_e32 v130, v2
	v_mov_b32_e32 v131, v2
	v_mov_b32_e32 v132, v2
	v_mov_b32_e32 v133, v2
	v_mov_b32_e32 v134, v2
	v_mov_b32_e32 v135, v2
	v_mov_b32_e32 v136, v2
	v_mov_b32_e32 v137, v2
	v_mov_b32_e32 v74, v2
	v_mov_b32_e32 v75, v2
	v_mov_b32_e32 v76, v2
	v_mov_b32_e32 v77, v2
	v_mov_b32_e32 v78, v2
	v_mov_b32_e32 v79, v2
	v_mov_b32_e32 v80, v2
	v_mov_b32_e32 v81, v2
	v_mov_b32_e32 v90, v2
	v_mov_b32_e32 v91, v2
	v_mov_b32_e32 v92, v2
	v_mov_b32_e32 v93, v2
	v_mov_b32_e32 v94, v2
	v_mov_b32_e32 v95, v2
	v_mov_b32_e32 v96, v2
	v_mov_b32_e32 v97, v2
	v_mov_b32_e32 v122, v2
	v_mov_b32_e32 v123, v2
	v_mov_b32_e32 v124, v2
	v_mov_b32_e32 v125, v2
	v_mov_b32_e32 v126, v2
	v_mov_b32_e32 v127, v2
	v_mov_b32_e32 v128, v2
	v_mov_b32_e32 v129, v2
	v_mov_b32_e32 v138, v2
	v_mov_b32_e32 v139, v2
	v_mov_b32_e32 v140, v2
	v_mov_b32_e32 v141, v2
	v_mov_b32_e32 v142, v2
	v_mov_b32_e32 v143, v2
	v_mov_b32_e32 v144, v2
	v_mov_b32_e32 v145, v2
	v_readlane_b32 s75, v254, 13

.LBB0_573:
	s_ashr_i32 s13, s12, 31
	s_lshl_b64 s[14:15], s[12:13], 18
	s_add_u32 s14, s30, s14
	s_addc_u32 s15, s31, s15
	s_and_b64 s[16:17], s[2:3], exec
	s_cselect_b32 s13, s15, s23
	s_cselect_b32 s46, s14, s22
	s_ashr_i32 s11, s10, 31
	s_lshl_b64 s[16:17], s[10:11], 18
	v_readlane_b32 s68, v254, 4
	s_add_u32 s16, s68, s16
	s_addc_u32 s17, s78, s17
	s_and_b64 s[26:27], s[2:3], exec
	s_cselect_b32 s11, s17, s25
	s_cselect_b32 s47, s16, s24
	s_add_u32 s22, s22, 0x20080
	s_addc_u32 s23, s23, 0
	s_add_u32 s56, s24, 0x100
	v_mov_b32_e32 v2, 0
	s_addc_u32 s57, s25, 0
	s_mov_b32 s66, -2
	v_mov_b32_e32 v3, v2
	v_mov_b32_e32 v4, v2
	v_mov_b32_e32 v5, v2
	v_mov_b32_e32 v6, v2
	v_mov_b32_e32 v7, v2
	v_mov_b32_e32 v8, v2
	v_mov_b32_e32 v9, v2
	v_mov_b32_e32 v18, v2
	v_mov_b32_e32 v19, v2
	v_mov_b32_e32 v20, v2
	v_mov_b32_e32 v21, v2
	v_mov_b32_e32 v22, v2
	v_mov_b32_e32 v23, v2
	v_mov_b32_e32 v24, v2
	v_mov_b32_e32 v25, v2
	v_mov_b32_e32 v34, v2
	v_mov_b32_e32 v35, v2
	v_mov_b32_e32 v36, v2
	v_mov_b32_e32 v37, v2
	v_mov_b32_e32 v38, v2
	v_mov_b32_e32 v39, v2
	v_mov_b32_e32 v40, v2
	v_mov_b32_e32 v41, v2
	v_mov_b32_e32 v50, v2
	v_mov_b32_e32 v51, v2
	v_mov_b32_e32 v52, v2
	v_mov_b32_e32 v53, v2
	v_mov_b32_e32 v54, v2
	v_mov_b32_e32 v55, v2
	v_mov_b32_e32 v56, v2
	v_mov_b32_e32 v57, v2
	v_mov_b32_e32 v10, v2
	v_mov_b32_e32 v11, v2
	v_mov_b32_e32 v12, v2
	v_mov_b32_e32 v13, v2
	v_mov_b32_e32 v14, v2
	v_mov_b32_e32 v15, v2
	v_mov_b32_e32 v16, v2
	v_mov_b32_e32 v17, v2
	v_mov_b32_e32 v26, v2
	v_mov_b32_e32 v27, v2
	v_mov_b32_e32 v28, v2
	v_mov_b32_e32 v29, v2
	v_mov_b32_e32 v30, v2
	v_mov_b32_e32 v31, v2
	v_mov_b32_e32 v32, v2
	v_mov_b32_e32 v33, v2
	v_mov_b32_e32 v42, v2
	v_mov_b32_e32 v43, v2
	v_mov_b32_e32 v44, v2
	v_mov_b32_e32 v45, v2
	v_mov_b32_e32 v46, v2
	v_mov_b32_e32 v47, v2
	v_mov_b32_e32 v48, v2
	v_mov_b32_e32 v49, v2
	v_mov_b32_e32 v58, v2
	v_mov_b32_e32 v59, v2
	v_mov_b32_e32 v60, v2
	v_mov_b32_e32 v61, v2
	v_mov_b32_e32 v62, v2
	v_mov_b32_e32 v63, v2
	v_mov_b32_e32 v64, v2
	v_mov_b32_e32 v65, v2
	v_mov_b32_e32 v66, v2
	v_mov_b32_e32 v67, v2
	v_mov_b32_e32 v68, v2
	v_mov_b32_e32 v69, v2
	v_mov_b32_e32 v70, v2
	v_mov_b32_e32 v71, v2
	v_mov_b32_e32 v72, v2
	v_mov_b32_e32 v73, v2
	v_mov_b32_e32 v82, v2
	v_mov_b32_e32 v83, v2
	v_mov_b32_e32 v84, v2
	v_mov_b32_e32 v85, v2
	v_mov_b32_e32 v86, v2
	v_mov_b32_e32 v87, v2
	v_mov_b32_e32 v88, v2
	v_mov_b32_e32 v89, v2
	v_mov_b32_e32 v114, v2
	v_mov_b32_e32 v115, v2
	v_mov_b32_e32 v116, v2
	v_mov_b32_e32 v117, v2
	v_mov_b32_e32 v118, v2
	v_mov_b32_e32 v119, v2
	v_mov_b32_e32 v120, v2
	v_mov_b32_e32 v121, v2
	v_mov_b32_e32 v130, v2
	v_mov_b32_e32 v131, v2
	v_mov_b32_e32 v132, v2
	v_mov_b32_e32 v133, v2
	v_mov_b32_e32 v134, v2
	v_mov_b32_e32 v135, v2
	v_mov_b32_e32 v136, v2
	v_mov_b32_e32 v137, v2
	v_mov_b32_e32 v74, v2
	v_mov_b32_e32 v75, v2
	v_mov_b32_e32 v76, v2
	v_mov_b32_e32 v77, v2
	v_mov_b32_e32 v78, v2
	v_mov_b32_e32 v79, v2
	v_mov_b32_e32 v80, v2
	v_mov_b32_e32 v81, v2
	v_mov_b32_e32 v106, v2
	v_mov_b32_e32 v107, v2
	v_mov_b32_e32 v108, v2
	v_mov_b32_e32 v109, v2
	v_mov_b32_e32 v110, v2
	v_mov_b32_e32 v111, v2
	v_mov_b32_e32 v112, v2
	v_mov_b32_e32 v113, v2
	v_mov_b32_e32 v122, v2
	v_mov_b32_e32 v123, v2
	v_mov_b32_e32 v124, v2
	v_mov_b32_e32 v125, v2
	v_mov_b32_e32 v126, v2
	v_mov_b32_e32 v127, v2
	v_mov_b32_e32 v128, v2
	v_mov_b32_e32 v129, v2
	v_mov_b32_e32 v138, v2
	v_mov_b32_e32 v139, v2
	v_mov_b32_e32 v140, v2
	v_mov_b32_e32 v141, v2
	v_mov_b32_e32 v94, v2
	v_mov_b32_e32 v95, v2
	v_mov_b32_e32 v96, v2
	v_mov_b32_e32 v97, v2
	v_readlane_b32 s69, v254, 5
	v_readlane_b32 s70, v254, 6
	v_readlane_b32 s71, v254, 7

.LBB0_936:
	s_ashr_i32 s21, s20, 31
	s_lshl_b64 s[22:23], s[20:21], 23
	s_add_u32 s22, s48, s22
	s_addc_u32 s23, s49, s23
	s_and_b64 s[24:25], s[2:3], exec
	s_cselect_b32 s21, s23, s29
	s_cselect_b32 s66, s22, s28
	s_ashr_i32 s19, s18, 31
	s_lshl_b64 s[24:25], s[18:19], 23
	s_add_u32 s24, s44, s24
	s_addc_u32 s25, s45, s25
	s_and_b64 s[34:35], s[2:3], exec
	s_cselect_b32 s19, s25, s31
	s_cselect_b32 s67, s24, s30
	s_add_u32 s28, s28, 0x400080
	s_addc_u32 s29, s29, 0
	s_add_u32 s68, s30, 0x100
	v_mov_b32_e32 v0, 0
	s_addc_u32 s69, s31, 0
	s_mov_b32 s70, -2
	v_mov_b32_e32 v1, v0
	v_mov_b32_e32 v2, v0
	v_mov_b32_e32 v3, v0
	v_mov_b32_e32 v4, v0
	v_mov_b32_e32 v5, v0
	v_mov_b32_e32 v6, v0
	v_mov_b32_e32 v7, v0
	v_mov_b32_e32 v8, v0
	v_mov_b32_e32 v9, v0
	v_mov_b32_e32 v10, v0
	v_mov_b32_e32 v11, v0
	v_mov_b32_e32 v16, v0
	v_mov_b32_e32 v17, v0
	v_mov_b32_e32 v18, v0
	v_mov_b32_e32 v19, v0
	v_mov_b32_e32 v24, v0
	v_mov_b32_e32 v25, v0
	v_mov_b32_e32 v26, v0
	v_mov_b32_e32 v27, v0
	v_mov_b32_e32 v32, v0
	v_mov_b32_e32 v33, v0
	v_mov_b32_e32 v34, v0
	v_mov_b32_e32 v35, v0
	v_mov_b32_e32 v40, v0
	v_mov_b32_e32 v41, v0
	v_mov_b32_e32 v42, v0
	v_mov_b32_e32 v43, v0
	v_mov_b32_e32 v48, v0
	v_mov_b32_e32 v49, v0
	v_mov_b32_e32 v50, v0
	v_mov_b32_e32 v51, v0
	v_mov_b32_e32 v12, v0
	v_mov_b32_e32 v13, v0
	v_mov_b32_e32 v14, v0
	v_mov_b32_e32 v15, v0
	v_mov_b32_e32 v20, v0
	v_mov_b32_e32 v21, v0
	v_mov_b32_e32 v22, v0
	v_mov_b32_e32 v23, v0
	v_mov_b32_e32 v28, v0
	v_mov_b32_e32 v29, v0
	v_mov_b32_e32 v30, v0
	v_mov_b32_e32 v31, v0
	v_mov_b32_e32 v36, v0
	v_mov_b32_e32 v37, v0
	v_mov_b32_e32 v38, v0
	v_mov_b32_e32 v39, v0
	v_mov_b32_e32 v44, v0
	v_mov_b32_e32 v45, v0
	v_mov_b32_e32 v46, v0
	v_mov_b32_e32 v47, v0
	v_mov_b32_e32 v52, v0
	v_mov_b32_e32 v53, v0
	v_mov_b32_e32 v54, v0
	v_mov_b32_e32 v55, v0
	v_mov_b32_e32 v56, v0
	v_mov_b32_e32 v57, v0
	v_mov_b32_e32 v58, v0
	v_mov_b32_e32 v59, v0
	v_mov_b32_e32 v60, v0
	v_mov_b32_e32 v61, v0
	v_mov_b32_e32 v62, v0
	v_mov_b32_e32 v63, v0
	v_mov_b32_e32 v64, v0
	v_mov_b32_e32 v65, v0
	v_mov_b32_e32 v66, v0
	v_mov_b32_e32 v67, v0
	v_mov_b32_e32 v68, v0
	v_mov_b32_e32 v69, v0
	v_mov_b32_e32 v70, v0
	v_mov_b32_e32 v71, v0
	v_mov_b32_e32 v80, v0
	v_mov_b32_e32 v81, v0
	v_mov_b32_e32 v82, v0
	v_mov_b32_e32 v83, v0
	v_mov_b32_e32 v84, v0
	v_mov_b32_e32 v85, v0
	v_mov_b32_e32 v86, v0
	v_mov_b32_e32 v87, v0
	v_mov_b32_e32 v88, v0
	v_mov_b32_e32 v89, v0
	v_mov_b32_e32 v90, v0
	v_mov_b32_e32 v91, v0
	v_mov_b32_e32 v92, v0
	v_mov_b32_e32 v93, v0
	v_mov_b32_e32 v94, v0
	v_mov_b32_e32 v95, v0
	v_mov_b32_e32 v96, v0
	v_mov_b32_e32 v97, v0
	v_mov_b32_e32 v98, v0
	v_mov_b32_e32 v99, v0
	v_mov_b32_e32 v104, v0
	v_mov_b32_e32 v105, v0
	v_mov_b32_e32 v106, v0
	v_mov_b32_e32 v107, v0
	v_mov_b32_e32 v72, v0
	v_mov_b32_e32 v73, v0
	v_mov_b32_e32 v74, v0
	v_mov_b32_e32 v75, v0
	v_mov_b32_e32 v76, v0
	v_mov_b32_e32 v77, v0
	v_mov_b32_e32 v78, v0
	v_mov_b32_e32 v79, v0
	v_mov_b32_e32 v100, v0
	v_mov_b32_e32 v101, v0
	v_mov_b32_e32 v102, v0
	v_mov_b32_e32 v103, v0
	v_mov_b32_e32 v108, v0
	v_mov_b32_e32 v109, v0
	v_mov_b32_e32 v110, v0
	v_mov_b32_e32 v111, v0
	v_mov_b32_e32 v112, v0
	v_mov_b32_e32 v113, v0
	v_mov_b32_e32 v114, v0
	v_mov_b32_e32 v115, v0
	v_mov_b32_e32 v116, v0
	v_mov_b32_e32 v117, v0
	v_mov_b32_e32 v118, v0
	v_mov_b32_e32 v119, v0
	v_mov_b32_e32 v120, v0
	v_mov_b32_e32 v121, v0
	v_mov_b32_e32 v122, v0
	v_mov_b32_e32 v123, v0
	v_mov_b32_e32 v124, v0
	v_mov_b32_e32 v125, v0
	v_mov_b32_e32 v126, v0
	v_mov_b32_e32 v127, v0
